# P7 M-wave sleep behind the LDS read issue retuned 18 -> 15 (probe suggested -13us, possibly noise)
# baseline (speedup 1.0000x reference)
; #define LAS __attribute__((address_space(3)))
;     ...
;     const LAS unsigned char* qrow = base + OFF_Q + (16 * ti + l16) * QS + kq * 16;
;     const LAS unsigned char* krow = base + OFF_K + l16 * QS + kq * 16;
;     const LAS unsigned char* srow = lds + OFF_ST + SET * ST_BYTES + l16 * QS + kq * 16;
;     const LAS unsigned char* vrow = base + OFF_VT + l16 * TS;
; #pragma unroll
;     for (int kk = 0; kk < 4; ++kk) { qf[kk] = *(const LAS bf16x8*)(qrow + kk * 64); sb[0][kk] = *(const LAS bf16x8*)(srow + kk * 64); sb[1][kk] = *(const LAS bf16x8*)(srow + 16 * QS + kk * 64); }
; #pragma unroll
;     for (int si = 0; si < 4; ++si)
; #pragma unroll
;         for (int kk = 0; kk < 4; ++kk) kf[si][kk] = *(const LAS bf16x8*)(krow + si * 16 * QS + kk * 64);
; #pragma unroll
;     for (int vh = 0; vh < 2; ++vh)
; #pragma unroll
;         for (int p = 0; p < 2; ++p) { va[vh][p] = *(const LAS u32x2*)(vrow + vh * 16 * TS + kq * 8 + p * 64); vb2[vh][p] = *(const LAS u32x2*)(vrow + vh * 16 * TS + kq * 8 + p * 64 + 32); }
; #pragma unroll
;     for (int kk = 0; kk < 2; ++kk) { vv[0][kk] = *(const LAS bf16x8*)(vrow + kk * 64 + kq * 16); vv[1][kk] = *(const LAS bf16x8*)(vrow + 16 * TS + kk * 64 + kq * 16);
;         kt[0][kk] = *(const LAS bf16x8*)(base + OFF_KT + (32 * ti + l16) * TS + kk * 64 + kq * 16); kt[1][kk] = *(const LAS bf16x8*)(base + OFF_KT + (32 * ti + 16 + l16) * TS + kk * 64 + kq * 16); }
;     dl[0] = *(const LAS f32x4*)(base + OFF_DL + (32 * ti + 4 * kq) * 4); dl[1] = *(const LAS f32x4*)(base + OFF_DL + (32 * ti + 16 + 4 * kq) * 4);
;     __builtin_amdgcn_sched_barrier(0);
;     f32x4 o[2], as[4];
;     o[0] = (f32x4){0.f, 0.f, 0.f, 0.f}; o[1] = o[0];
; #pragma unroll
;     for (int si = 0; si < 4; ++si) as[si] = (f32x4){0.f, 0.f, 0.f, 0.f};
; #pragma unroll
;     for (int kk = 0; kk < 4; ++kk) { o[0] = MFMA16(qf[kk], sb[0][kk], o[0]); o[1] = MFMA16(qf[kk], sb[1][kk], o[1]);
; #pragma unroll
;         for (int si = 0; si < 4; ++si) as[si] = MFMA16(kf[si][kk], qf[kk], as[si]); }
; #pragma unroll
;     for (int ds = 0; ds < 2; ++ds)
; #pragma unroll
;         for (int vh = 0; vh < 2; ++vh) { st[ds][vh] = st[ds][vh] * dl[ds];
; #pragma unroll
;             for (int kk = 0; kk < 2; ++kk) st[ds][vh] = MFMA16(kt[ds][kk], vv[vh][kk], st[ds][vh]); }
;     const int tq = 16 * ti + l16 - 4 * kq;
; #pragma unroll
;     for (int si = 0; si < 4; ++si)
; #pragma unroll
.LBB0_1179:
	v_add_u32_e32 v28, v117, v84
	ds_read_b128 v[100:103], v99
	ds_read_b128 v[104:107], v99 offset:64
	ds_read_b128 v[108:111], v28
	ds_read_b128 v[138:141], v28 offset:64
	ds_read_b128 v[142:145], v28 offset:4352
	ds_read_b128 v[146:149], v28 offset:4416
	ds_read_b128 v[48:51], v99 offset:128
	ds_read_b128 v[24:27], v99 offset:192
	ds_read_b128 v[56:59], v28 offset:128
	ds_read_b128 v[32:35], v28 offset:192
	ds_read_b128 v[150:153], v28 offset:4480
	ds_read_b128 v[52:55], v28 offset:4544
	v_add_u32_e32 v28, v116, v84
	ds_read_b128 v[154:157], v28 offset:17408
	ds_read_b128 v[158:161], v28 offset:17472
	ds_read_b128 v[162:165], v28 offset:17536
	ds_read_b128 v[60:63], v28 offset:17600
	ds_read_b128 v[166:169], v28 offset:21760
	ds_read_b128 v[170:173], v28 offset:21824
	ds_read_b128 v[174:177], v28 offset:21888
	ds_read_b128 v[64:67], v28 offset:21952
	ds_read_b128 v[178:181], v28 offset:26112
	ds_read_b128 v[182:185], v28 offset:26176
	ds_read_b128 v[186:189], v28 offset:26240
	ds_read_b128 v[68:71], v28 offset:26304
	ds_read_b128 v[190:193], v28 offset:30464
	ds_read_b128 v[194:197], v28 offset:30528
	ds_read_b128 v[76:79], v28 offset:30592
	ds_read_b128 v[72:75], v28 offset:30656
	v_add_u32_e32 v36, v118, v119
	v_add_u32_e32 v28, 0xd000, v36
	v_add_u32_e32 v36, 0xd800, v36
	v_add_u32_e32 v112, v118, v84
	ds_read2_b64 v[40:43], v28 offset1:4
	ds_read2_b64 v[28:31], v28 offset0:8 offset1:12
	ds_read2_b64 v[44:47], v36 offset0:32 offset1:36
	ds_read2_b64 v[36:39], v36 offset0:40 offset1:44
	v_add_u32_e32 v113, v115, v89
	ds_read_b128 v[202:205], v112 offset:53248
	ds_read_b128 v[208:211], v112 offset:53312
	ds_read_b128 v[212:215], v112 offset:55552
	ds_read_b128 v[216:219], v112 offset:55616
	ds_read_b128 v[220:223], v113 offset:34816
	ds_read_b128 v[224:227], v113 offset:34880
	ds_read_b128 v[228:231], v113 offset:37120
	ds_read_b128 v[232:235], v113 offset:37184
	ds_read_b128 v[236:239], v95 offset:57856
	ds_read_b128 v[240:243], v95 offset:57920
	s_add_i32 s3, s3, 2
	s_sleep 15
	s_waitcnt lgkmcnt(14)
	v_mfma_f32_16x16x32_bf16 v[142:145], v[142:145], v[100:103], 0
	s_waitcnt lgkmcnt(1)
	v_pk_mul_f32 v[20:21], v[20:21], v[236:237]
	v_pk_mul_f32 v[22:23], v[22:23], v[238:239]
	v_pk_mul_f32 v[8:9], v[8:9], v[236:237]
	v_mfma_f32_16x16x32_bf16 v[154:157], v[154:157], v[100:103], 0
	v_mul_f32_e64 v10, v10, v238
	v_mul_f32_e64 v11, v11, v239
	s_waitcnt lgkmcnt(0)
	v_pk_mul_f32 v[16:17], v[16:17], v[240:241]
	v_pk_mul_f32 v[18:19], v[18:19], v[242:243]
	v_mfma_f32_16x16x32_bf16 v[166:169], v[166:169], v[100:103], 0
	v_mul_f32_e64 v12, v12, v240
	v_mul_f32_e64 v13, v13, v241
	v_pk_mul_f32 v[14:15], v[14:15], v[242:243]
	s_movk_i32 s0, 0x1000
	v_mfma_f32_16x16x32_bf16 v[178:181], v[178:181], v[100:103], 0
	v_add_co_u32_e32 v112, vcc, s0, v92
	s_movk_i32 s0, 0x3000
	v_mfma_f32_16x16x32_bf16 v[190:193], v[190:193], v[100:103], 0
	v_addc_co_u32_e32 v113, vcc, 0, v93, vcc
	v_mfma_f32_16x16x32_bf16 v[100:103], v[108:111], v[100:103], 0
	v_mfma_f32_16x16x32_bf16 v[108:111], v[220:223], v[212:215], v[20:23]
	v_mfma_f32_16x16x32_bf16 v[142:145], v[146:149], v[104:107], v[142:145]
	v_mfma_f32_16x16x32_bf16 v[146:149], v[158:161], v[104:107], v[154:157]
	v_mfma_f32_16x16x32_bf16 v[154:157], v[170:173], v[104:107], v[166:169]
	v_mfma_f32_16x16x32_bf16 v[8:11], v[220:223], v[202:205], v[8:11]
	v_mfma_f32_16x16x32_bf16 v[202:205], v[228:231], v[202:205], v[16:19]
	v_mfma_f32_16x16x32_bf16 v[158:161], v[182:185], v[104:107], v[178:181]
	v_mfma_f32_16x16x32_bf16 v[166:169], v[194:197], v[104:107], v[190:193]
	v_mfma_f32_16x16x32_bf16 v[100:103], v[138:141], v[104:107], v[100:103]
	v_mfma_f32_16x16x32_bf16 v[16:19], v[224:227], v[216:219], v[108:111]
	v_mfma_f32_16x16x32_bf16 v[108:111], v[162:165], v[48:51], v[146:149]
	v_mfma_f32_16x16x32_bf16 v[138:141], v[174:177], v[48:51], v[154:157]
	s_nop 1
	v_add_co_u32_e32 v146, vcc, s67, v92
	v_mfma_f32_16x16x32_bf16 v[212:215], v[228:231], v[212:215], v[12:15]
	s_nop 0
	v_addc_co_u32_e32 v147, vcc, 0, v93, vcc
	v_add_co_u32_e32 v148, vcc, s0, v92
	v_mfma_f32_16x16x32_bf16 v[104:107], v[150:153], v[48:51], v[142:145]
	v_add_u32_e32 v152, v121, v94
	s_min_u32 s0, s3, 0x7c
	s_lshl_b32 s48, s0, 18
	v_mfma_f32_16x16x32_bf16 v[142:145], v[186:189], v[48:51], v[158:161]
	v_addc_co_u32_e32 v149, vcc, 0, v93, vcc
	v_lshl_add_u64 v[150:151], v[90:91], 0, s[48:49]
	v_mfma_f32_16x16x32_bf16 v[76:79], v[76:79], v[48:51], v[166:169]
	s_mov_b32 s0, 0xc0000
	v_add_co_u32_e32 v150, vcc, s0, v150
	v_mfma_f32_16x16x32_bf16 v[48:51], v[56:59], v[48:51], v[100:103]
	s_nop 0
	v_addc_co_u32_e32 v151, vcc, 0, v151, vcc
	v_mfma_f32_16x16x32_bf16 v[56:59], v[60:63], v[24:27], v[108:111]
	v_cvt_pk_bf16_f32 v102, v16, v17
	v_cvt_pk_bf16_f32 v103, v18, v19
	v_mfma_f32_16x16x32_bf16 v[60:63], v[64:67], v[24:27], v[138:141]
	v_mfma_f32_16x16x32_bf16 v[20:23], v[224:227], v[208:211], v[8:11]
	s_nop 3
	v_cndmask_b32_e64 v58, v58, 0, s[20:21]
	s_nop 1
	v_cndmask_b32_e64 v62, v62, 0, s[28:29]
	v_cndmask_b32_e64 v60, v60, 0, s[24:25]
	v_mfma_f32_16x16x32_bf16 v[8:11], v[232:235], v[216:219], v[212:215]
	v_cndmask_b32_e64 v56, v56, 0, s[64:65]
	v_cvt_pk_bf16_f32 v100, v20, v21
	v_cvt_pk_bf16_f32 v101, v22, v23
	v_mfma_f32_16x16x32_bf16 v[52:55], v[52:55], v[24:27], v[104:107]
	v_mfma_f32_16x16x32_bf16 v[64:67], v[68:71], v[24:27], v[142:145]
	s_nop 2
	v_cvt_pk_bf16_f32 v106, v8, v9
	v_cvt_pk_bf16_f32 v107, v10, v11
	v_mfma_f32_16x16x32_bf16 v[68:71], v[72:75], v[24:27], v[76:79]
	v_mfma_f32_16x16x32_bf16 v[24:27], v[32:35], v[24:27], v[48:51]
	v_cndmask_b32_e64 v35, v63, 0, s[30:31]
	v_cndmask_b32_e64 v34, v61, 0, s[26:27]
	v_cndmask_b32_e64 v33, v59, 0, s[22:23]
	v_cndmask_b32_e64 v32, v57, 0, s[16:17]
	v_mfma_f32_16x16x32_bf16 v[12:15], v[232:235], v[208:211], v[202:205]
	v_cvt_pk_bf16_f32 v32, v56, v32
	v_cvt_pk_bf16_f32 v33, v58, v33
	v_cvt_pk_bf16_f32 v34, v60, v34
	v_cvt_pk_bf16_f32 v35, v62, v35
	v_cndmask_b32_e64 v48, v69, 0, s[44:45]
	s_nop 2
	v_cvt_pk_bf16_f32 v104, v12, v13
	v_cvt_pk_bf16_f32 v105, v14, v15
	ds_write_b64 v152, v[100:101]
	ds_write_b64 v152, v[102:103] offset:4352
	ds_write_b64 v96, v[104:105]
	ds_write_b64 v96, v[106:107] offset:4352
	s_waitcnt vmcnt(3)
; #define LAS __attribute__((address_space(3)))
; #define MFMA16(a, b, c) __builtin_amdgcn_mfma_f32_16x16x32_bf16((a), (b), (c), 0, 0, 0)
;     ...
;     const LAS unsigned char* qrow = base + OFF_Q + (16 * ti + l16) * QS + kq * 16;
;     const LAS unsigned char* krow = base + OFF_K + l16 * QS + kq * 16;
;     const LAS unsigned char* srow = lds + OFF_ST + SET * ST_BYTES + l16 * QS + kq * 16;
;     const LAS unsigned char* vrow = base + OFF_VT + l16 * TS;
; #pragma unroll
;     for (int kk = 0; kk < 4; ++kk) { qf[kk] = *(const LAS bf16x8*)(qrow + kk * 64); sb[0][kk] = *(const LAS bf16x8*)(srow + kk * 64); sb[1][kk] = *(const LAS bf16x8*)(srow + 16 * QS + kk * 64); }
; #pragma unroll
;     for (int si = 0; si < 4; ++si)
; #pragma unroll
;         for (int kk = 0; kk < 4; ++kk) kf[si][kk] = *(const LAS bf16x8*)(krow + si * 16 * QS + kk * 64);
; #pragma unroll
;     for (int vh = 0; vh < 2; ++vh)
; #pragma unroll
;         for (int p = 0; p < 2; ++p) { va[vh][p] = *(const LAS u32x2*)(vrow + vh * 16 * TS + kq * 8 + p * 64); vb2[vh][p] = *(const LAS u32x2*)(vrow + vh * 16 * TS + kq * 8 + p * 64 + 32); }
; #pragma unroll
;     for (int kk = 0; kk < 2; ++kk) { vv[0][kk] = *(const LAS bf16x8*)(vrow + kk * 64 + kq * 16); vv[1][kk] = *(const LAS bf16x8*)(vrow + 16 * TS + kk * 64 + kq * 16);
;     ...
;     for (int p = 0; p < 2; ++p) {
;         u32x4 pw; pw.x = cvtpk_s(as[2 * p][0], as[2 * p][1]); pw.y = cvtpk_s(as[2 * p][2], as[2 * p][3]); pw.z = cvtpk_s(as[2 * p + 1][0], as[2 * p + 1][1]); pw.w = cvtpk_s(as[2 * p + 1][2], as[2 * p + 1][3]);
; #pragma unroll
;         for (int vh = 0; vh < 2; ++vh) { const u32x4 vw = {va[vh][p].x, va[vh][p].y, vb2[vh][p].x, vb2[vh][p].y};
;             o[vh] = MFMA16(__builtin_bit_cast(bf16x8, pw), __builtin_bit_cast(bf16x8, vw), o[vh]); }
;     }
;     if ((VAR & 1) == 0 || o[0][0] == 12345.678f) {
; #pragma unroll
;     for (int vh = 0; vh < 2; ++vh)
; #pragma unroll
;         for (int j = 0; j < 4; ++j) *(bf16r*)(ob + (size_t)j * DM * 2 + vh * 32 + ol) = (bf16r)(cvtpk_s(o[vh][j], 0.f) & 0xffffu);
;     }
; #pragma unroll
;     for (int ds = 0; ds < 2; ++ds)
; #pragma unroll
;         for (int vh = 0; vh < 2; ++vh)
;             *(LAS u32x2*)(lds + OFF_ST + (SET ^ 1) * ST_BYTES + (16 * vh + l16) * QS + (32 * ti + 16 * ds + 4 * kq) * 2) = (u32x2){cvtpk_s(st[ds][vh][0], st[ds][vh][1]), cvtpk_s(st[ds][vh][2], st[ds][vh][3])};
; }
	ds_write_b16 v136, v0
	ds_write_b16_d16_hi v136, v0 offset:144
	ds_write_b16 v136, v1 offset:288
	ds_write_b16_d16_hi v136, v1 offset:432
	ds_write_b16 v136, v2 offset:576
	v_cndmask_b32_e64 v0, v71, 0, s[14:15]
	v_cndmask_b32_e64 v1, v70, 0, s[46:47]
	v_cndmask_b32_e64 v49, v68, 0, s[42:43]
	v_cndmask_b32_e64 v50, v67, 0, s[40:41]
	v_cndmask_b32_e64 v51, v66, 0, s[38:39]
	v_cndmask_b32_e64 v65, v65, 0, s[36:37]
	v_cndmask_b32_e64 v64, v64, 0, s[34:35]
	v_mfma_f32_16x16x32_bf16 v[24:27], v[40:43], v[32:35], v[24:27]
	v_cvt_pk_bf16_f32 v40, v64, v65
	v_cvt_pk_bf16_f32 v41, v51, v50
	v_cvt_pk_bf16_f32 v42, v49, v48
	v_cvt_pk_bf16_f32 v43, v1, v0
	v_mfma_f32_16x16x32_bf16 v[32:35], v[44:47], v[32:35], v[52:55]
	ds_write_b16_d16_hi v136, v2 offset:720
	ds_write_b16 v136, v3 offset:864
	ds_write_b16_d16_hi v136, v3 offset:1008
	v_mfma_f32_16x16x32_bf16 v[24:27], v[28:31], v[40:43], v[24:27]
	v_mfma_f32_16x16x32_bf16 v[0:3], v[36:39], v[40:43], v[32:35]
	s_nop 6
	v_cvt_pk_bf16_f32 v24, v24, v25
	v_cvt_pk_bf16_f32 v25, v26, v27
	v_cvt_pk_bf16_f32 v26, v0, v1
	v_cvt_pk_bf16_f32 v27, v2, v3
	global_store_dwordx2 v[244:245], v[24:25], off
	global_store_dwordx2 v[244:245], v[26:27], off offset:32
	global_load_dwordx4 v[0:3], v[150:151], off
	v_add_u32_e32 v25, v122, v119
	v_add_u32_e32 v24, v121, v84
	v_add_u32_e32 v26, 0x800, v25
	s_waitcnt lgkmcnt(0)
	s_barrier
	v_add_u32_e32 v112, v122, v84
	v_add_u32_e32 v113, 0x1c600, v95
	ds_read_b128 v[100:103], v99 offset:58368
	ds_read_b128 v[104:107], v99 offset:58432
	ds_read_b128 v[108:111], v24
	ds_read_b128 v[138:141], v24 offset:64
	ds_read_b128 v[142:145], v24 offset:4352
	ds_read_b128 v[146:149], v24 offset:4416
	ds_read_b128 v[68:71], v99 offset:58496
	ds_read_b128 v[36:39], v99 offset:58560
	ds_read_b128 v[72:75], v24 offset:128
	ds_read_b128 v[44:47], v24 offset:192
	ds_read_b128 v[150:153], v24 offset:4480
	ds_read_b128 v[48:51], v24 offset:4544
	ds_read_b128 v[154:157], v137
	ds_read_b128 v[158:161], v137 offset:64
	ds_read_b128 v[162:165], v137 offset:128
	ds_read_b128 v[52:55], v137 offset:192
	ds_read_b128 v[166:169], v137 offset:4352
	ds_read_b128 v[170:173], v137 offset:4416
	ds_read_b128 v[174:177], v137 offset:4480
	ds_read_b128 v[56:59], v137 offset:4544
	ds_read_b128 v[178:181], v137 offset:8704
	ds_read_b128 v[182:185], v137 offset:8768
	ds_read_b128 v[186:189], v137 offset:8832
	ds_read_b128 v[60:63], v137 offset:8896
	ds_read_b128 v[190:193], v137 offset:13056
	ds_read_b128 v[194:197], v137 offset:13120
	ds_read_b128 v[76:79], v137 offset:13184
	ds_read_b128 v[64:67], v137 offset:13248
	ds_read2_b64 v[40:43], v25 offset1:4
	ds_read2_b64 v[28:31], v25 offset0:8 offset1:12
	ds_read2_b64 v[32:35], v26 offset0:32 offset1:36
	ds_read2_b64 v[24:27], v26 offset0:40 offset1:44
	ds_read_b128 v[202:205], v112
	ds_read_b128 v[208:211], v112 offset:64
	ds_read_b128 v[212:215], v112 offset:2304
	ds_read_b128 v[216:219], v112 offset:2368
	ds_read_b128 v[220:223], v97
	ds_read_b128 v[224:227], v97 offset:64
	ds_read_b128 v[228:231], v97 offset:2304
	ds_read_b128 v[232:235], v97 offset:2368
	ds_read_b128 v[236:239], v113
	ds_read_b128 v[240:243], v113 offset:64
	s_sleep 15
	s_waitcnt lgkmcnt(14)
	v_mfma_f32_16x16x32_bf16 v[142:145], v[142:145], v[100:103], 0
	s_waitcnt lgkmcnt(1)
	v_pk_mul_f32 v[22:23], v[22:23], v[238:239]
	v_pk_mul_f32 v[20:21], v[20:21], v[236:237]
	v_pk_mul_f32 v[18:19], v[18:19], v[238:239]
	v_mfma_f32_16x16x32_bf16 v[154:157], v[154:157], v[100:103], 0
	v_mul_f32_e64 v16, v16, v236
	v_mul_f32_e64 v17, v17, v237
	s_waitcnt lgkmcnt(0)
; #define LAS __attribute__((address_space(3)))
;     ...
;     for (int kk = 0; kk < 4; ++kk) { o[0] = MFMA16(qf[kk], sb[0][kk], o[0]); o[1] = MFMA16(qf[kk], sb[1][kk], o[1]);
; #pragma unroll
;         for (int si = 0; si < 4; ++si) as[si] = MFMA16(kf[si][kk], qf[kk], as[si]); }
; #pragma unroll
;     for (int ds = 0; ds < 2; ++ds)
; #pragma unroll
;         for (int vh = 0; vh < 2; ++vh) { st[ds][vh] = st[ds][vh] * dl[ds];
; #pragma unroll
;             for (int kk = 0; kk < 2; ++kk) st[ds][vh] = MFMA16(kt[ds][kk], vv[vh][kk], st[ds][vh]); }
;     const int tq = 16 * ti + l16 - 4 * kq;
; #pragma unroll
;     for (int si = 0; si < 4; ++si)
; #pragma unroll
;         for (int j = 0; j < 4; ++j) if (16 * si + j > tq) as[si][j] = 0.f;
; #pragma unroll
;     for (int p = 0; p < 2; ++p) {
;         u32x4 pw; pw.x = cvtpk_s(as[2 * p][0], as[2 * p][1]); pw.y = cvtpk_s(as[2 * p][2], as[2 * p][3]); pw.z = cvtpk_s(as[2 * p + 1][0], as[2 * p + 1][1]); pw.w = cvtpk_s(as[2 * p + 1][2], as[2 * p + 1][3]);
; #pragma unroll
;         for (int vh = 0; vh < 2; ++vh) { const u32x4 vw = {va[vh][p].x, va[vh][p].y, vb2[vh][p].x, vb2[vh][p].y};
;             o[vh] = MFMA16(__builtin_bit_cast(bf16x8, pw), __builtin_bit_cast(bf16x8, vw), o[vh]); }
;     }
;     if ((VAR & 1) == 0 || o[0][0] == 12345.678f) {
; #pragma unroll
;     for (int vh = 0; vh < 2; ++vh)
; #pragma unroll
;         for (int j = 0; j < 4; ++j) *(bf16r*)(ob + (size_t)j * DM * 2 + vh * 32 + ol) = (bf16r)(cvtpk_s(o[vh][j], 0.f) & 0xffffu);
;     }
; #pragma unroll
;     for (int ds = 0; ds < 2; ++ds)
; #pragma unroll
;         for (int vh = 0; vh < 2; ++vh)
;             *(LAS u32x2*)(lds + OFF_ST + (SET ^ 1) * ST_BYTES + (16 * vh + l16) * QS + (32 * ti + 16 * ds + 4 * kq) * 2) = (u32x2){cvtpk_s(st[ds][vh][0], st[ds][vh][1]), cvtpk_s(st[ds][vh][2], st[ds][vh][3])};
; }
;     ...
;         for (int c = 0; c < NC; c += 2) {
;             if ((VAR & 4) == 0) hgM<0, VAR>(lds, st, ti, lane, ob + (size_t)c * 64 * DM * 2, ol);
;             hgV<1>(lds, vB, mt); vB = *(const u32x4*)(vp + (size_t)(c + 3 < NC ? c + 3 : NC - 1) * 64 * DM);
;             HBAR();
;             if ((VAR & 4) == 0) hgM<1, VAR>(lds, st, ti, lane, ob + (size_t)(c + 1) * 64 * DM * 2, ol);
;             hgV<0>(lds, vA, mt); vA = *(const u32x4*)(vp + (size_t)(c + 4 < NC ? c + 4 : NC - 1) * 64 * DM);
;             HBAR();
;         }
	v_pk_mul_f32 v[14:15], v[14:15], v[242:243]
	v_pk_mul_f32 v[12:13], v[12:13], v[240:241]
	v_mfma_f32_16x16x32_bf16 v[166:169], v[166:169], v[100:103], 0
	v_mul_f32_e64 v10, v10, v242
	v_mul_f32_e64 v11, v11, v243
	v_pk_mul_f32 v[8:9], v[8:9], v[240:241]
	s_mov_b32 s0, 0x40000
	v_mfma_f32_16x16x32_bf16 v[178:181], v[178:181], v[100:103], 0
	v_add_co_u32_e32 v112, vcc, s0, v92
	s_mov_b32 s0, 0x42000
	v_mfma_f32_16x16x32_bf16 v[190:193], v[190:193], v[100:103], 0
	v_addc_co_u32_e32 v113, vcc, 0, v93, vcc
	v_mfma_f32_16x16x32_bf16 v[100:103], v[108:111], v[100:103], 0
	v_mfma_f32_16x16x32_bf16 v[20:23], v[220:223], v[202:205], v[20:23]
	v_mfma_f32_16x16x32_bf16 v[16:19], v[220:223], v[212:215], v[16:19]
	v_mfma_f32_16x16x32_bf16 v[12:15], v[228:231], v[202:205], v[12:15]
	v_mfma_f32_16x16x32_bf16 v[108:111], v[228:231], v[212:215], v[8:11]
	v_mfma_f32_16x16x32_bf16 v[142:145], v[146:149], v[104:107], v[142:145]
	v_mfma_f32_16x16x32_bf16 v[146:149], v[158:161], v[104:107], v[154:157]
	v_mfma_f32_16x16x32_bf16 v[154:157], v[170:173], v[104:107], v[166:169]
	v_mfma_f32_16x16x32_bf16 v[158:161], v[182:185], v[104:107], v[178:181]
	v_mfma_f32_16x16x32_bf16 v[166:169], v[194:197], v[104:107], v[190:193]
	v_mfma_f32_16x16x32_bf16 v[100:103], v[138:141], v[104:107], v[100:103]
	v_mfma_f32_16x16x32_bf16 v[8:11], v[224:227], v[208:211], v[20:23]
	v_mfma_f32_16x16x32_bf16 v[20:23], v[224:227], v[216:219], v[16:19]
	v_mfma_f32_16x16x32_bf16 v[16:19], v[232:235], v[208:211], v[12:15]
	v_mfma_f32_16x16x32_bf16 v[12:15], v[232:235], v[216:219], v[108:111]
	v_mfma_f32_16x16x32_bf16 v[108:111], v[162:165], v[68:71], v[146:149]
	v_mfma_f32_16x16x32_bf16 v[138:141], v[174:177], v[68:71], v[154:157]
	v_mfma_f32_16x16x32_bf16 v[104:107], v[150:153], v[68:71], v[142:145]
	s_nop 1
	v_add_u32_e32 v154, v117, v94
	v_add_co_u32_e32 v150, vcc, s70, v92
	v_mfma_f32_16x16x32_bf16 v[142:145], v[186:189], v[68:71], v[158:161]
	s_nop 0
	v_addc_co_u32_e32 v151, vcc, 0, v93, vcc
	v_add_co_u32_e32 v146, vcc, s0, v92
	v_mfma_f32_16x16x32_bf16 v[76:79], v[76:79], v[68:71], v[166:169]
	s_nop 0
	v_addc_co_u32_e32 v147, vcc, 0, v93, vcc
	s_min_u32 s0, s3, 0x7b
	v_mfma_f32_16x16x32_bf16 v[68:71], v[72:75], v[68:71], v[100:103]
	v_cvt_pk_bf16_f32 v72, v8, v9
	v_cvt_pk_bf16_f32 v73, v10, v11
	v_cvt_pk_bf16_f32 v74, v20, v21
	v_mfma_f32_16x16x32_bf16 v[52:55], v[52:55], v[36:39], v[108:111]
	v_cvt_pk_bf16_f32 v102, v12, v13
	v_cvt_pk_bf16_f32 v103, v14, v15
	v_cvt_pk_bf16_f32 v75, v22, v23
	v_mfma_f32_16x16x32_bf16 v[56:59], v[56:59], v[36:39], v[138:141]
	v_cvt_pk_bf16_f32 v100, v16, v17
	s_nop 2
	v_cndmask_b32_e64 v54, v54, 0, s[20:21]
	v_cndmask_b32_e64 v52, v52, 0, s[64:65]
	v_mfma_f32_16x16x32_bf16 v[48:51], v[48:51], v[36:39], v[104:107]
	v_cvt_pk_bf16_f32 v101, v18, v19
	v_cndmask_b32_e64 v58, v58, 0, s[28:29]
	v_cndmask_b32_e64 v56, v56, 0, s[24:25]
	v_mfma_f32_16x16x32_bf16 v[60:63], v[60:63], v[36:39], v[142:145]
	ds_write_b64 v154, v[72:73]
	ds_write_b64 v154, v[74:75] offset:4352
	ds_write_b64 v98, v[100:101]
	ds_write_b64 v98, v[102:103] offset:4352
	s_waitcnt vmcnt(3)
	ds_write_b16 v135, v4 offset:53248
	ds_write_b16_d16_hi v135, v4 offset:53392
	ds_write_b16 v135, v5 offset:53536
	ds_write_b16_d16_hi v135, v5 offset:53680
	ds_write_b16 v135, v6 offset:53824
	v_mfma_f32_16x16x32_bf16 v[64:67], v[64:67], v[36:39], v[76:79]
	v_cndmask_b32_e64 v63, v63, 0, s[40:41]
	v_cndmask_b32_e64 v62, v62, 0, s[38:39]
	v_cndmask_b32_e64 v61, v61, 0, s[36:37]
	v_mfma_f32_16x16x32_bf16 v[36:39], v[44:47], v[36:39], v[68:71]
	v_cndmask_b32_e64 v47, v59, 0, s[30:31]
	v_cndmask_b32_e64 v46, v57, 0, s[26:27]
	v_cndmask_b32_e64 v45, v55, 0, s[22:23]
	v_cndmask_b32_e64 v44, v53, 0, s[16:17]
	v_cvt_pk_bf16_f32 v44, v52, v44
	v_cvt_pk_bf16_f32 v45, v54, v45
	v_cvt_pk_bf16_f32 v46, v56, v46
	v_cvt_pk_bf16_f32 v47, v58, v47
	v_cndmask_b32_e64 v4, v67, 0, s[14:15]
	v_cndmask_b32_e64 v5, v66, 0, s[46:47]
	v_cndmask_b32_e64 v65, v65, 0, s[44:45]
	v_cndmask_b32_e64 v64, v64, 0, s[42:43]
	v_cndmask_b32_e64 v60, v60, 0, s[34:35]
	v_mfma_f32_16x16x32_bf16 v[36:39], v[40:43], v[44:47], v[36:39]
	v_cvt_pk_bf16_f32 v40, v60, v61
	v_cvt_pk_bf16_f32 v41, v62, v63
	v_cvt_pk_bf16_f32 v42, v64, v65
	v_cvt_pk_bf16_f32 v43, v5, v4
	v_mfma_f32_16x16x32_bf16 v[32:35], v[32:35], v[44:47], v[48:51]
	ds_write_b16_d16_hi v135, v6 offset:53968
	ds_write_b16 v135, v7 offset:54112
	ds_write_b16_d16_hi v135, v7 offset:54256
	v_add_co_u32_e32 v148, vcc, s71, v92
	v_mfma_f32_16x16x32_bf16 v[28:31], v[28:31], v[40:43], v[36:39]
	s_lshl_b32 s48, s0, 18
	v_addc_co_u32_e32 v149, vcc, 0, v93, vcc
	v_mfma_f32_16x16x32_bf16 v[4:7], v[24:27], v[40:43], v[32:35]
	v_lshl_add_u64 v[152:153], v[90:91], 0, s[48:49]
	v_add_co_u32_e32 v152, vcc, 0x100000, v152
	s_nop 2
	v_cvt_pk_bf16_f32 v24, v28, v29
	v_addc_co_u32_e32 v153, vcc, 0, v153, vcc
	v_cvt_pk_bf16_f32 v25, v30, v31
	v_cvt_pk_bf16_f32 v26, v4, v5
	v_cvt_pk_bf16_f32 v27, v6, v7
	global_store_dwordx2 v[246:247], v[24:25], off
	global_store_dwordx2 v[246:247], v[26:27], off offset:32
	global_load_dwordx4 v[4:7], v[152:153], off
	s_waitcnt lgkmcnt(0)
	s_barrier
	s_mov_b64 s[0:1], 0x80000
	s_cmpk_lt_u32 s3, 0x7e
	v_lshl_add_u64 v[92:93], v[92:93], 0, s[0:1]
	v_lshl_add_u64 v[244:245], v[244:245], 0, s[0:1]
	v_lshl_add_u64 v[246:247], v[246:247], 0, s[0:1]
	s_cbranch_scc1 .LBB0_1179
	s_mov_b64 s[16:17], 0
